# top-k popcount accumulation split between scalar and vector units; indexer score pairs share one row swap, fewer VALU per tile
# speedup vs baseline: 1.0415x; 1.0018x over previous
; __device__ __forceinline__ f32x4 mfma16(bf16x8 a, bf16x8 b, f32x4 c) { return __builtin_amdgcn_mfma_f32_16x16x32_bf16(a, b, c, 0, 0, 0); }
; __device__ __forceinline__ void indexer_unit(const Args& a, LAS unsigned char* lds, LAS unsigned long long* maskl, int b, int qblk, int wave, int lane) {
;     ...
; #pragma unroll
;         for (int rt = 0; rt < 8; ++rt) {
;             f32x4 acc = {0.f, 0.f, 0.f, 0.f};
;             __builtin_amdgcn_s_setprio(1); acc = mfma16(af[rt][0], b0, acc); acc = mfma16(af[rt][1], b1, acc); __builtin_amdgcn_s_setprio(0);
;             float part = wv[rt][0] * fmaxf(acc[0], 0.f) + wv[rt][1] * fmaxf(acc[1], 0.f) + wv[rt][2] * fmaxf(acc[2], 0.f) + wv[rt][3] * fmaxf(acc[3], 0.f);
;             part += __shfl_xor(part, 16); part += 0.f;
;             if ((fq & 1) == 0) sc[(2 * rt + (fq >> 1)) * 2048 + key] = part;
;         }
.LBB0_1085:
	s_mov_b32 s11, s10
	s_add_i32 s10, s10, 8
	s_cmp_gt_u32 s10, s9
	s_cselect_b64 s[2:3], -1, 0
	s_and_b64 s[4:5], s[2:3], exec
	s_cselect_b32 s4, s11, s10
	v_lshl_add_u32 v74, s4, 4, v117
	v_mov_b32_e32 v75, v4
	v_lshlrev_b64 v[74:75], 7, v[74:75]
	v_lshl_add_u64 v[78:79], v[82:83], 0, v[74:75]
	global_load_dwordx4 v[74:77], v[78:79], off
	s_nop 0
	global_load_dwordx4 v[78:81], v[78:79], off offset:64
	s_setprio 1
	v_mfma_f32_16x16x32_bf16 v[128:131], v[0:3], v[70:73], 0
	v_mfma_f32_16x16x32_bf16 v[132:135], v[14:17], v[70:73], 0
	v_mfma_f32_16x16x32_bf16 v[136:139], v[18:21], v[70:73], 0
	v_mfma_f32_16x16x32_bf16 v[140:143], v[30:33], v[70:73], 0
	v_mfma_f32_16x16x32_bf16 v[144:147], v[34:37], v[70:73], 0
	v_mfma_f32_16x16x32_bf16 v[148:151], v[42:45], v[70:73], 0
	v_mfma_f32_16x16x32_bf16 v[152:155], v[54:57], v[70:73], 0
	v_mfma_f32_16x16x32_bf16 v[156:159], v[46:49], v[70:73], 0
	v_mfma_f32_16x16x32_bf16 v[128:131], v[6:9], v[66:69], v[128:131]
	v_mfma_f32_16x16x32_bf16 v[132:135], v[10:13], v[66:69], v[132:135]
	v_mfma_f32_16x16x32_bf16 v[136:139], v[22:25], v[66:69], v[136:139]
	v_mfma_f32_16x16x32_bf16 v[140:143], v[26:29], v[66:69], v[140:143]
	v_mfma_f32_16x16x32_bf16 v[144:147], v[38:41], v[66:69], v[144:147]
	v_mfma_f32_16x16x32_bf16 v[148:151], v[50:53], v[66:69], v[148:151]
	v_mfma_f32_16x16x32_bf16 v[152:155], v[58:61], v[66:69], v[152:155]
	v_mfma_f32_16x16x32_bf16 v[156:159], v[62:65], v[66:69], v[156:159]
	s_setprio 0
	s_nop 1
	v_max_f32_e32 v160, 0, v128
	v_max_f32_e32 v168, 0, v129
	v_fma_f32 v168, v168, v86, 0
	v_max_f32_e32 v161, 0, v130
	v_fmac_f32_e32 v168, v160, v85
	v_max_f32_e32 v160, 0, v131
	v_fmac_f32_e32 v168, v161, v87
	v_fmac_f32_e32 v168, v160, v88
	v_max_f32_e32 v160, 0, v132
	v_max_f32_e32 v169, 0, v133
	v_fma_f32 v169, v169, v90, 0
	v_max_f32_e32 v161, 0, v134
	v_fmac_f32_e32 v169, v160, v89
	v_max_f32_e32 v160, 0, v135
	v_fmac_f32_e32 v169, v161, v91
	v_fmac_f32_e32 v169, v160, v92
	v_max_f32_e32 v160, 0, v136
	v_max_f32_e32 v170, 0, v137
	v_fma_f32 v170, v170, v94, 0
	v_max_f32_e32 v161, 0, v138
	v_fmac_f32_e32 v170, v160, v93
	v_max_f32_e32 v160, 0, v139
	v_fmac_f32_e32 v170, v161, v95
	v_fmac_f32_e32 v170, v160, v96
	v_max_f32_e32 v160, 0, v140
	v_max_f32_e32 v171, 0, v141
	v_fma_f32 v171, v171, v98, 0
	v_max_f32_e32 v161, 0, v142
	v_fmac_f32_e32 v171, v160, v97
	v_max_f32_e32 v160, 0, v143
	v_fmac_f32_e32 v171, v161, v99
	v_fmac_f32_e32 v171, v160, v100
	v_max_f32_e32 v160, 0, v144
	v_max_f32_e32 v172, 0, v145
	v_fma_f32 v172, v172, v102, 0
	v_max_f32_e32 v161, 0, v146
	v_fmac_f32_e32 v172, v160, v101
	v_max_f32_e32 v160, 0, v147
	v_fmac_f32_e32 v172, v161, v103
	v_fmac_f32_e32 v172, v160, v104
	v_max_f32_e32 v160, 0, v148
	v_max_f32_e32 v173, 0, v149
	v_fma_f32 v173, v173, v106, 0
	v_max_f32_e32 v161, 0, v150
	v_fmac_f32_e32 v173, v160, v105
	v_max_f32_e32 v160, 0, v151
	v_fmac_f32_e32 v173, v161, v107
	v_fmac_f32_e32 v173, v160, v108
	v_max_f32_e32 v160, 0, v152
	v_max_f32_e32 v174, 0, v153
	v_fma_f32 v174, v174, v110, 0
	v_max_f32_e32 v161, 0, v154
	v_fmac_f32_e32 v174, v160, v109
	v_max_f32_e32 v160, 0, v155
	v_fmac_f32_e32 v174, v161, v111
	v_fmac_f32_e32 v174, v160, v112
	v_max_f32_e32 v160, 0, v156
	v_max_f32_e32 v175, 0, v157
	v_fma_f32 v175, v175, v114, 0
	v_max_f32_e32 v161, 0, v158
	v_fmac_f32_e32 v175, v160, v113
	v_max_f32_e32 v160, 0, v159
	v_fmac_f32_e32 v175, v161, v115
	v_fmac_f32_e32 v175, v160, v116
	s_nop 0
	v_permlane16_swap_b32_e32 v168, v172
	v_permlane16_swap_b32_e32 v169, v173
	v_permlane16_swap_b32_e32 v170, v174
	v_permlane16_swap_b32_e32 v171, v175
	v_add_f32_e32 v168, v168, v172
	v_add_f32_e32 v169, v169, v173
	v_add_f32_e32 v170, v170, v174
	v_add_f32_e32 v171, v171, v175
	v_and_b32_e32 v160, 16, v252
	v_lshl_add_u32 v160, v160, 12, v119
	ds_write_b32 v160, v168
	ds_write_b32 v160, v169 offset:16384
	ds_write_b32 v160, v170 offset:32768
	ds_write_b32 v160, v171 offset:49152
	s_branch .LBB0_1084

; #define TK_GRP(g) { const int c0 = __popcll(__ballot(u[4 * (g)] >= cand)), c1 = __popcll(__ballot(u[4 * (g) + 1] >= cand)), c2 = __popcll(__ballot(u[4 * (g) + 2] >= cand)), c3 = __popcll(__ballot(u[4 * (g) + 3] >= cand)); cnt += (c0 + c1) + (c2 + c3); }
; __device__ __forceinline__ void indexer_unit(const Args& a, LAS unsigned char* lds, LAS unsigned long long* maskl, int b, int qblk, int wave, int lane) {
;     ...
;                 const unsigned cand = T | (1u << bit); int cnt = 0;
;     ...
;                 switch (ng) {
;                     case 8: TK_GRP(7) [[fallthrough]];
;                     case 7: TK_GRP(6) [[fallthrough]];
;                     case 6: TK_GRP(5) [[fallthrough]];
;                     case 5: TK_GRP(4) [[fallthrough]];
;                     case 4: TK_GRP(3) [[fallthrough]];
;                     case 3: TK_GRP(2) [[fallthrough]];
;                     case 2: TK_GRP(1) [[fallthrough]];
;                     default: TK_GRP(0)
;                 }
;     ...
;                 if (cnt >= 256) { T = cand; if (cnt == 256) { exact = true; break; } }
;             }
;             int need = 0; const unsigned long long lt = (1ull << lane) - 1ull;
;             if (!exact) {
;                 int cl = 0;
; #pragma unroll
;                 for (int r = 0; r < 32; ++r) cl += (u[r] > T) ? 1 : 0;
;                 int ngt = 0;
; #pragma unroll
;                 for (int bb = 0; bb < 6; ++bb) ngt += __popcll(__ballot((cl >> bb) & 1)) << bb;
;                 need = 256 - ngt;
.Ltk_bit:
	s_lshl_b32 s12, 1, s11
	s_or_b32 s13, s10, s12
	v_mov_b32_e32 v24, 0
	v_cmp_le_u32_e64 s[24:25], s13, v32
	v_cmp_le_u32_e64 s[26:27], s13, v33
	v_cmp_le_u32_e64 s[28:29], s13, v34
	v_cmp_le_u32_e64 s[30:31], s13, v35
	v_cmp_le_u32_e64 s[34:35], s13, v36
	v_cmp_le_u32_e64 s[36:37], s13, v37
	v_cmp_le_u32_e64 s[38:39], s13, v38
	v_cmp_le_u32_e64 s[40:41], s13, v39
	s_bcnt1_i32_b64 s42, s[24:25]
	s_bcnt1_i32_b64 s43, s[26:27]
	s_bcnt1_i32_b64 s44, s[28:29]
	s_bcnt1_i32_b64 s45, s[30:31]
	s_bcnt1_i32_b64 s46, s[34:35]
	s_bcnt1_i32_b64 s47, s[36:37]
	s_bcnt1_i32_b64 s48, s[38:39]
	s_bcnt1_i32_b64 s49, s[40:41]
	s_add_i32 s14, s42, s43
	v_add_u32_e32 v24, s44, v24
	v_add_u32_e32 v24, s45, v24
	v_add_u32_e32 v24, s46, v24
	v_add_u32_e32 v24, s47, v24
	v_add_u32_e32 v24, s48, v24
	v_add_u32_e32 v24, s49, v24
	s_cmp_lt_u32 s21, 2
	s_cbranch_scc1 .Ltk_dec
	v_cmp_le_u32_e64 s[24:25], s13, v40
	v_cmp_le_u32_e64 s[26:27], s13, v41
	v_cmp_le_u32_e64 s[28:29], s13, v42
	v_cmp_le_u32_e64 s[30:31], s13, v43
	v_cmp_le_u32_e64 s[34:35], s13, v44
	v_cmp_le_u32_e64 s[36:37], s13, v45
	v_cmp_le_u32_e64 s[38:39], s13, v46
	v_cmp_le_u32_e64 s[40:41], s13, v47
	s_bcnt1_i32_b64 s42, s[24:25]
	s_bcnt1_i32_b64 s43, s[26:27]
	s_bcnt1_i32_b64 s44, s[28:29]
	s_bcnt1_i32_b64 s45, s[30:31]
	s_bcnt1_i32_b64 s46, s[34:35]
	s_bcnt1_i32_b64 s47, s[36:37]
	s_bcnt1_i32_b64 s48, s[38:39]
	s_bcnt1_i32_b64 s49, s[40:41]
	s_add_i32 s14, s14, s42
	s_add_i32 s14, s14, s43
	v_add_u32_e32 v24, s44, v24
	v_add_u32_e32 v24, s45, v24
	v_add_u32_e32 v24, s46, v24
	v_add_u32_e32 v24, s47, v24
	v_add_u32_e32 v24, s48, v24
	v_add_u32_e32 v24, s49, v24
	s_cmp_lt_u32 s21, 3
	s_cbranch_scc1 .Ltk_dec
	v_cmp_le_u32_e64 s[24:25], s13, v48
	v_cmp_le_u32_e64 s[26:27], s13, v49
	v_cmp_le_u32_e64 s[28:29], s13, v50
	v_cmp_le_u32_e64 s[30:31], s13, v51
	v_cmp_le_u32_e64 s[34:35], s13, v52
	v_cmp_le_u32_e64 s[36:37], s13, v53
	v_cmp_le_u32_e64 s[38:39], s13, v54
	v_cmp_le_u32_e64 s[40:41], s13, v55
	s_bcnt1_i32_b64 s42, s[24:25]
	s_bcnt1_i32_b64 s43, s[26:27]
	s_bcnt1_i32_b64 s44, s[28:29]
	s_bcnt1_i32_b64 s45, s[30:31]
	s_bcnt1_i32_b64 s46, s[34:35]
	s_bcnt1_i32_b64 s47, s[36:37]
	s_bcnt1_i32_b64 s48, s[38:39]
	s_bcnt1_i32_b64 s49, s[40:41]
	s_add_i32 s14, s14, s42
	s_add_i32 s14, s14, s43
	v_add_u32_e32 v24, s44, v24
	v_add_u32_e32 v24, s45, v24
	v_add_u32_e32 v24, s46, v24
	v_add_u32_e32 v24, s47, v24
	v_add_u32_e32 v24, s48, v24
	v_add_u32_e32 v24, s49, v24
	s_cmp_lt_u32 s21, 4
	s_cbranch_scc1 .Ltk_dec
	v_cmp_le_u32_e64 s[24:25], s13, v56
	v_cmp_le_u32_e64 s[26:27], s13, v57
	v_cmp_le_u32_e64 s[28:29], s13, v58
	v_cmp_le_u32_e64 s[30:31], s13, v59
	v_cmp_le_u32_e64 s[34:35], s13, v60
	v_cmp_le_u32_e64 s[36:37], s13, v61
	v_cmp_le_u32_e64 s[38:39], s13, v62
	v_cmp_le_u32_e64 s[40:41], s13, v63
	s_bcnt1_i32_b64 s42, s[24:25]
	s_bcnt1_i32_b64 s43, s[26:27]
	s_bcnt1_i32_b64 s44, s[28:29]
	s_bcnt1_i32_b64 s45, s[30:31]
	s_bcnt1_i32_b64 s46, s[34:35]
	s_bcnt1_i32_b64 s47, s[36:37]
	s_bcnt1_i32_b64 s48, s[38:39]
	s_bcnt1_i32_b64 s49, s[40:41]
	s_add_i32 s14, s14, s42
	s_add_i32 s14, s14, s43
	v_add_u32_e32 v24, s44, v24
	v_add_u32_e32 v24, s45, v24
	v_add_u32_e32 v24, s46, v24
	v_add_u32_e32 v24, s47, v24
	v_add_u32_e32 v24, s48, v24
	v_add_u32_e32 v24, s49, v24
.Ltk_dec:
	s_nop 0
	v_readfirstlane_b32 s15, v24
	s_add_i32 s14, s14, s15
	s_cmpk_lt_u32 s14, 0x100
	s_cbranch_scc1 .Ltk_nxt
	s_mov_b32 s10, s13
	s_cmpk_eq_u32 s14, 0x100
	s_cbranch_scc1 .Ltk_exact
.Ltk_nxt:
	s_add_i32 s11, s11, -1
	s_cmp_ge_i32 s11, 0
	s_cbranch_scc1 .Ltk_bit
	v_mov_b32_e32 v0, 0
	v_mov_b32_e32 v1, 0
	v_mov_b32_e32 v24, 0
	v_cmp_lt_u32_e64 s[24:25], s10, v32
	v_cmp_lt_u32_e64 s[26:27], s10, v33
	v_cmp_lt_u32_e64 s[28:29], s10, v34
	v_cmp_lt_u32_e64 s[30:31], s10, v35
	v_cmp_lt_u32_e64 s[34:35], s10, v36
	v_cmp_lt_u32_e64 s[36:37], s10, v37
	v_cmp_lt_u32_e64 s[38:39], s10, v38
	v_cmp_lt_u32_e64 s[40:41], s10, v39
	s_bcnt1_i32_b64 s42, s[24:25]
	s_bcnt1_i32_b64 s43, s[26:27]
	s_bcnt1_i32_b64 s44, s[28:29]
	s_bcnt1_i32_b64 s45, s[30:31]
	s_bcnt1_i32_b64 s46, s[34:35]
	s_bcnt1_i32_b64 s47, s[36:37]
	s_bcnt1_i32_b64 s48, s[38:39]
	s_bcnt1_i32_b64 s49, s[40:41]
	s_add_i32 s14, s42, s43
	v_add_u32_e32 v24, s44, v24
	v_add_u32_e32 v24, s45, v24
	v_add_u32_e32 v24, s46, v24
	v_add_u32_e32 v24, s47, v24
	v_add_u32_e32 v24, s48, v24
	v_add_u32_e32 v24, s49, v24
	s_cmp_lt_u32 s21, 2
	s_cbranch_scc1 .Ltk_tie_cnt_done
	v_cmp_lt_u32_e64 s[24:25], s10, v40
	v_cmp_lt_u32_e64 s[26:27], s10, v41
	v_cmp_lt_u32_e64 s[28:29], s10, v42
	v_cmp_lt_u32_e64 s[30:31], s10, v43
	v_cmp_lt_u32_e64 s[34:35], s10, v44
	v_cmp_lt_u32_e64 s[36:37], s10, v45
	v_cmp_lt_u32_e64 s[38:39], s10, v46
	v_cmp_lt_u32_e64 s[40:41], s10, v47
	s_bcnt1_i32_b64 s42, s[24:25]
	s_bcnt1_i32_b64 s43, s[26:27]
	s_bcnt1_i32_b64 s44, s[28:29]
	s_bcnt1_i32_b64 s45, s[30:31]
	s_bcnt1_i32_b64 s46, s[34:35]
	s_bcnt1_i32_b64 s47, s[36:37]
	s_bcnt1_i32_b64 s48, s[38:39]
	s_bcnt1_i32_b64 s49, s[40:41]
	s_add_i32 s14, s14, s42
	s_add_i32 s14, s14, s43
	v_add_u32_e32 v24, s44, v24
	v_add_u32_e32 v24, s45, v24
	v_add_u32_e32 v24, s46, v24
	v_add_u32_e32 v24, s47, v24
	v_add_u32_e32 v24, s48, v24
	v_add_u32_e32 v24, s49, v24
	s_cmp_lt_u32 s21, 3
	s_cbranch_scc1 .Ltk_tie_cnt_done
	v_cmp_lt_u32_e64 s[24:25], s10, v48
	v_cmp_lt_u32_e64 s[26:27], s10, v49
	v_cmp_lt_u32_e64 s[28:29], s10, v50
	v_cmp_lt_u32_e64 s[30:31], s10, v51
	v_cmp_lt_u32_e64 s[34:35], s10, v52
	v_cmp_lt_u32_e64 s[36:37], s10, v53
	v_cmp_lt_u32_e64 s[38:39], s10, v54
	v_cmp_lt_u32_e64 s[40:41], s10, v55
	s_bcnt1_i32_b64 s42, s[24:25]
	s_bcnt1_i32_b64 s43, s[26:27]
	s_bcnt1_i32_b64 s44, s[28:29]
	s_bcnt1_i32_b64 s45, s[30:31]
	s_bcnt1_i32_b64 s46, s[34:35]
	s_bcnt1_i32_b64 s47, s[36:37]
	s_bcnt1_i32_b64 s48, s[38:39]
	s_bcnt1_i32_b64 s49, s[40:41]
	s_add_i32 s14, s14, s42
	s_add_i32 s14, s14, s43
	v_add_u32_e32 v24, s44, v24
	v_add_u32_e32 v24, s45, v24
	v_add_u32_e32 v24, s46, v24
	v_add_u32_e32 v24, s47, v24
	v_add_u32_e32 v24, s48, v24
	v_add_u32_e32 v24, s49, v24
	s_cmp_lt_u32 s21, 4
	s_cbranch_scc1 .Ltk_tie_cnt_done
	v_cmp_lt_u32_e64 s[24:25], s10, v56
	v_cmp_lt_u32_e64 s[26:27], s10, v57
	v_cmp_lt_u32_e64 s[28:29], s10, v58
	v_cmp_lt_u32_e64 s[30:31], s10, v59
	v_cmp_lt_u32_e64 s[34:35], s10, v60
	v_cmp_lt_u32_e64 s[36:37], s10, v61
	v_cmp_lt_u32_e64 s[38:39], s10, v62
	v_cmp_lt_u32_e64 s[40:41], s10, v63
	s_bcnt1_i32_b64 s42, s[24:25]
	s_bcnt1_i32_b64 s43, s[26:27]
	s_bcnt1_i32_b64 s44, s[28:29]
	s_bcnt1_i32_b64 s45, s[30:31]
	s_bcnt1_i32_b64 s46, s[34:35]
	s_bcnt1_i32_b64 s47, s[36:37]
	s_bcnt1_i32_b64 s48, s[38:39]
	s_bcnt1_i32_b64 s49, s[40:41]
	s_add_i32 s14, s14, s42
	s_add_i32 s14, s14, s43
	v_add_u32_e32 v24, s44, v24
	v_add_u32_e32 v24, s45, v24
	v_add_u32_e32 v24, s46, v24
	v_add_u32_e32 v24, s47, v24
	v_add_u32_e32 v24, s48, v24
	v_add_u32_e32 v24, s49, v24
; __device__ __forceinline__ void indexer_unit(const Args& a, LAS unsigned char* lds, LAS unsigned long long* maskl, int b, int qblk, int wave, int lane) {
;     ...
;             int need = 0; const unsigned long long lt = (1ull << lane) - 1ull;
;             if (!exact) {
;                 int cl = 0;
; #pragma unroll
;                 for (int r = 0; r < 32; ++r) cl += (u[r] > T) ? 1 : 0;
;                 int ngt = 0;
; #pragma unroll
;                 for (int bb = 0; bb < 6; ++bb) ngt += __popcll(__ballot((cl >> bb) & 1)) << bb;
;                 need = 256 - ngt;
;             }
; #pragma unroll
;             for (int g = 0; g < 8; ++g) if (4 * g < nr) {
; #pragma unroll
;                 for (int k = 0; k < 4; ++k) { const int r = 4 * g + k;
;                     unsigned ur = u[r]; asm volatile("" : "+v"(ur), "+v"(myword), "+s"(need));
;                     unsigned long long m;
;                     if (exact) m = __ballot(ur >= T);
;                     else { const unsigned long long eq = __ballot(ur == T), gt = __ballot(ur > T);
;                         const bool pick = (ur == T) && (__popcll(eq & lt) < need);
;                         m = gt | __ballot(pick); need -= __popcll(eq); if (need < 0) need = 0; }
;                     if (lane == r) myword = m; } }
.Ltk_tie_cnt_done:
	s_nop 0
	v_readfirstlane_b32 s15, v24
	s_add_i32 s14, s14, s15
	s_sub_i32 s16, 0x100, s14
	v_cmp_eq_u32_e64 s[24:25], s10, v32
	v_cmp_lt_u32_e64 s[26:27], s10, v32
	s_bcnt1_i32_b64 s17, s[24:25]
	s_nop 0
	v_mbcnt_lo_u32_b32 v2, s24, 0
	v_mbcnt_hi_u32_b32 v2, s25, v2
	v_cmp_gt_u32_e64 s[28:29], s16, v2
	s_and_b64 s[28:29], s[28:29], s[24:25]
	s_or_b64 s[26:27], s[26:27], s[28:29]
	s_sub_i32 s16, s16, s17
	s_max_i32 s16, s16, 0
	v_writelane_b32 v0, s26, 0
	v_writelane_b32 v1, s27, 0
	v_cmp_eq_u32_e64 s[24:25], s10, v33
	v_cmp_lt_u32_e64 s[26:27], s10, v33
	s_bcnt1_i32_b64 s17, s[24:25]
	s_nop 0
	v_mbcnt_lo_u32_b32 v2, s24, 0
	v_mbcnt_hi_u32_b32 v2, s25, v2
	v_cmp_gt_u32_e64 s[28:29], s16, v2
	s_and_b64 s[28:29], s[28:29], s[24:25]
	s_or_b64 s[26:27], s[26:27], s[28:29]
	s_sub_i32 s16, s16, s17
	s_max_i32 s16, s16, 0
	v_writelane_b32 v0, s26, 1
	v_writelane_b32 v1, s27, 1
	v_cmp_eq_u32_e64 s[24:25], s10, v34
	v_cmp_lt_u32_e64 s[26:27], s10, v34
	s_bcnt1_i32_b64 s17, s[24:25]
	s_nop 0
	v_mbcnt_lo_u32_b32 v2, s24, 0
	v_mbcnt_hi_u32_b32 v2, s25, v2
	v_cmp_gt_u32_e64 s[28:29], s16, v2
	s_and_b64 s[28:29], s[28:29], s[24:25]
	s_or_b64 s[26:27], s[26:27], s[28:29]
	s_sub_i32 s16, s16, s17
	s_max_i32 s16, s16, 0
	v_writelane_b32 v0, s26, 2
	v_writelane_b32 v1, s27, 2
	v_cmp_eq_u32_e64 s[24:25], s10, v35
	v_cmp_lt_u32_e64 s[26:27], s10, v35
	s_bcnt1_i32_b64 s17, s[24:25]
	s_nop 0
	v_mbcnt_lo_u32_b32 v2, s24, 0
	v_mbcnt_hi_u32_b32 v2, s25, v2
	v_cmp_gt_u32_e64 s[28:29], s16, v2
	s_and_b64 s[28:29], s[28:29], s[24:25]
	s_or_b64 s[26:27], s[26:27], s[28:29]
	s_sub_i32 s16, s16, s17
	s_max_i32 s16, s16, 0
	v_writelane_b32 v0, s26, 3
	v_writelane_b32 v1, s27, 3
	v_cmp_eq_u32_e64 s[24:25], s10, v36
	v_cmp_lt_u32_e64 s[26:27], s10, v36
	s_bcnt1_i32_b64 s17, s[24:25]
	s_nop 0
	v_mbcnt_lo_u32_b32 v2, s24, 0
	v_mbcnt_hi_u32_b32 v2, s25, v2
	v_cmp_gt_u32_e64 s[28:29], s16, v2
	s_and_b64 s[28:29], s[28:29], s[24:25]
	s_or_b64 s[26:27], s[26:27], s[28:29]
	s_sub_i32 s16, s16, s17
	s_max_i32 s16, s16, 0
	v_writelane_b32 v0, s26, 4
	v_writelane_b32 v1, s27, 4
	v_cmp_eq_u32_e64 s[24:25], s10, v37
	v_cmp_lt_u32_e64 s[26:27], s10, v37
	s_bcnt1_i32_b64 s17, s[24:25]
	s_nop 0
	v_mbcnt_lo_u32_b32 v2, s24, 0
	v_mbcnt_hi_u32_b32 v2, s25, v2
	v_cmp_gt_u32_e64 s[28:29], s16, v2
	s_and_b64 s[28:29], s[28:29], s[24:25]
	s_or_b64 s[26:27], s[26:27], s[28:29]
	s_sub_i32 s16, s16, s17
	s_max_i32 s16, s16, 0
	v_writelane_b32 v0, s26, 5
	v_writelane_b32 v1, s27, 5
	v_cmp_eq_u32_e64 s[24:25], s10, v38
	v_cmp_lt_u32_e64 s[26:27], s10, v38
	s_bcnt1_i32_b64 s17, s[24:25]
	s_nop 0
	v_mbcnt_lo_u32_b32 v2, s24, 0
	v_mbcnt_hi_u32_b32 v2, s25, v2
	v_cmp_gt_u32_e64 s[28:29], s16, v2
	s_and_b64 s[28:29], s[28:29], s[24:25]
	s_or_b64 s[26:27], s[26:27], s[28:29]
	s_sub_i32 s16, s16, s17
	s_max_i32 s16, s16, 0
	v_writelane_b32 v0, s26, 6
	v_writelane_b32 v1, s27, 6
	v_cmp_eq_u32_e64 s[24:25], s10, v39
	v_cmp_lt_u32_e64 s[26:27], s10, v39
	s_bcnt1_i32_b64 s17, s[24:25]
	s_nop 0
	v_mbcnt_lo_u32_b32 v2, s24, 0
	v_mbcnt_hi_u32_b32 v2, s25, v2
	v_cmp_gt_u32_e64 s[28:29], s16, v2
	s_and_b64 s[28:29], s[28:29], s[24:25]
	s_or_b64 s[26:27], s[26:27], s[28:29]
	s_sub_i32 s16, s16, s17
	s_max_i32 s16, s16, 0
	v_writelane_b32 v0, s26, 7
	v_writelane_b32 v1, s27, 7
	s_cmp_lt_u32 s21, 2
	s_cbranch_scc1 .Ltk_store
	v_cmp_eq_u32_e64 s[24:25], s10, v40
	v_cmp_lt_u32_e64 s[26:27], s10, v40
	s_bcnt1_i32_b64 s17, s[24:25]
	s_nop 0
	v_mbcnt_lo_u32_b32 v2, s24, 0
	v_mbcnt_hi_u32_b32 v2, s25, v2
	v_cmp_gt_u32_e64 s[28:29], s16, v2
	s_and_b64 s[28:29], s[28:29], s[24:25]
	s_or_b64 s[26:27], s[26:27], s[28:29]
	s_sub_i32 s16, s16, s17
	s_max_i32 s16, s16, 0
	v_writelane_b32 v0, s26, 8
	v_writelane_b32 v1, s27, 8
	v_cmp_eq_u32_e64 s[24:25], s10, v41
	v_cmp_lt_u32_e64 s[26:27], s10, v41
	s_bcnt1_i32_b64 s17, s[24:25]
	s_nop 0
	v_mbcnt_lo_u32_b32 v2, s24, 0
	v_mbcnt_hi_u32_b32 v2, s25, v2
	v_cmp_gt_u32_e64 s[28:29], s16, v2
	s_and_b64 s[28:29], s[28:29], s[24:25]
	s_or_b64 s[26:27], s[26:27], s[28:29]
	s_sub_i32 s16, s16, s17
	s_max_i32 s16, s16, 0
	v_writelane_b32 v0, s26, 9
	v_writelane_b32 v1, s27, 9
	v_cmp_eq_u32_e64 s[24:25], s10, v42
	v_cmp_lt_u32_e64 s[26:27], s10, v42
	s_bcnt1_i32_b64 s17, s[24:25]
	s_nop 0
	v_mbcnt_lo_u32_b32 v2, s24, 0
	v_mbcnt_hi_u32_b32 v2, s25, v2
	v_cmp_gt_u32_e64 s[28:29], s16, v2
	s_and_b64 s[28:29], s[28:29], s[24:25]
	s_or_b64 s[26:27], s[26:27], s[28:29]
	s_sub_i32 s16, s16, s17
	s_max_i32 s16, s16, 0
	v_writelane_b32 v0, s26, 10
	v_writelane_b32 v1, s27, 10
	v_cmp_eq_u32_e64 s[24:25], s10, v43
	v_cmp_lt_u32_e64 s[26:27], s10, v43
	s_bcnt1_i32_b64 s17, s[24:25]
	s_nop 0
	v_mbcnt_lo_u32_b32 v2, s24, 0
	v_mbcnt_hi_u32_b32 v2, s25, v2
	v_cmp_gt_u32_e64 s[28:29], s16, v2
	s_and_b64 s[28:29], s[28:29], s[24:25]
	s_or_b64 s[26:27], s[26:27], s[28:29]
	s_sub_i32 s16, s16, s17
	s_max_i32 s16, s16, 0
	v_writelane_b32 v0, s26, 11
	v_writelane_b32 v1, s27, 11
	v_cmp_eq_u32_e64 s[24:25], s10, v44
	v_cmp_lt_u32_e64 s[26:27], s10, v44
	s_bcnt1_i32_b64 s17, s[24:25]
	s_nop 0
	v_mbcnt_lo_u32_b32 v2, s24, 0
	v_mbcnt_hi_u32_b32 v2, s25, v2
	v_cmp_gt_u32_e64 s[28:29], s16, v2
	s_and_b64 s[28:29], s[28:29], s[24:25]
	s_or_b64 s[26:27], s[26:27], s[28:29]
	s_sub_i32 s16, s16, s17
	s_max_i32 s16, s16, 0
	v_writelane_b32 v0, s26, 12
	v_writelane_b32 v1, s27, 12
	v_cmp_eq_u32_e64 s[24:25], s10, v45
	v_cmp_lt_u32_e64 s[26:27], s10, v45
	s_bcnt1_i32_b64 s17, s[24:25]
	s_nop 0
	v_mbcnt_lo_u32_b32 v2, s24, 0
	v_mbcnt_hi_u32_b32 v2, s25, v2
	v_cmp_gt_u32_e64 s[28:29], s16, v2
	s_and_b64 s[28:29], s[28:29], s[24:25]
	s_or_b64 s[26:27], s[26:27], s[28:29]
	s_sub_i32 s16, s16, s17
	s_max_i32 s16, s16, 0
	v_writelane_b32 v0, s26, 13
	v_writelane_b32 v1, s27, 13
	v_cmp_eq_u32_e64 s[24:25], s10, v46
	v_cmp_lt_u32_e64 s[26:27], s10, v46
	s_bcnt1_i32_b64 s17, s[24:25]
	s_nop 0
	v_mbcnt_lo_u32_b32 v2, s24, 0
	v_mbcnt_hi_u32_b32 v2, s25, v2
	v_cmp_gt_u32_e64 s[28:29], s16, v2
	s_and_b64 s[28:29], s[28:29], s[24:25]
	s_or_b64 s[26:27], s[26:27], s[28:29]
	s_sub_i32 s16, s16, s17
	s_max_i32 s16, s16, 0
	v_writelane_b32 v0, s26, 14
	v_writelane_b32 v1, s27, 14
	v_cmp_eq_u32_e64 s[24:25], s10, v47
	v_cmp_lt_u32_e64 s[26:27], s10, v47
	s_bcnt1_i32_b64 s17, s[24:25]
	s_nop 0
	v_mbcnt_lo_u32_b32 v2, s24, 0
	v_mbcnt_hi_u32_b32 v2, s25, v2
	v_cmp_gt_u32_e64 s[28:29], s16, v2
	s_and_b64 s[28:29], s[28:29], s[24:25]
	s_or_b64 s[26:27], s[26:27], s[28:29]
	s_sub_i32 s16, s16, s17
	s_max_i32 s16, s16, 0
	v_writelane_b32 v0, s26, 15
	v_writelane_b32 v1, s27, 15
	s_cmp_lt_u32 s21, 3
	s_cbranch_scc1 .Ltk_store
; __device__ __forceinline__ void indexer_unit(const Args& a, LAS unsigned char* lds, LAS unsigned long long* maskl, int b, int qblk, int wave, int lane) {
;     ...
; #pragma unroll
;             for (int g = 0; g < 8; ++g) if (4 * g < nr) {
; #pragma unroll
;                 for (int k = 0; k < 4; ++k) { const int r = 4 * g + k;
;                     unsigned ur = u[r]; asm volatile("" : "+v"(ur), "+v"(myword), "+s"(need));
;                     unsigned long long m;
;                     if (exact) m = __ballot(ur >= T);
;                     else { const unsigned long long eq = __ballot(ur == T), gt = __ballot(ur > T);
;                         const bool pick = (ur == T) && (__popcll(eq & lt) < need);
;                         m = gt | __ballot(pick); need -= __popcll(eq); if (need < 0) need = 0; }
;                     if (lane == r) myword = m; } }
	v_cmp_eq_u32_e64 s[24:25], s10, v48
	v_cmp_lt_u32_e64 s[26:27], s10, v48
	s_bcnt1_i32_b64 s17, s[24:25]
	s_nop 0
	v_mbcnt_lo_u32_b32 v2, s24, 0
	v_mbcnt_hi_u32_b32 v2, s25, v2
	v_cmp_gt_u32_e64 s[28:29], s16, v2
	s_and_b64 s[28:29], s[28:29], s[24:25]
	s_or_b64 s[26:27], s[26:27], s[28:29]
	s_sub_i32 s16, s16, s17
	s_max_i32 s16, s16, 0
	v_writelane_b32 v0, s26, 16
	v_writelane_b32 v1, s27, 16
	v_cmp_eq_u32_e64 s[24:25], s10, v49
	v_cmp_lt_u32_e64 s[26:27], s10, v49
	s_bcnt1_i32_b64 s17, s[24:25]
	s_nop 0
	v_mbcnt_lo_u32_b32 v2, s24, 0
	v_mbcnt_hi_u32_b32 v2, s25, v2
	v_cmp_gt_u32_e64 s[28:29], s16, v2
	s_and_b64 s[28:29], s[28:29], s[24:25]
	s_or_b64 s[26:27], s[26:27], s[28:29]
	s_sub_i32 s16, s16, s17
	s_max_i32 s16, s16, 0
	v_writelane_b32 v0, s26, 17
	v_writelane_b32 v1, s27, 17
	v_cmp_eq_u32_e64 s[24:25], s10, v50
	v_cmp_lt_u32_e64 s[26:27], s10, v50
	s_bcnt1_i32_b64 s17, s[24:25]
	s_nop 0
	v_mbcnt_lo_u32_b32 v2, s24, 0
	v_mbcnt_hi_u32_b32 v2, s25, v2
	v_cmp_gt_u32_e64 s[28:29], s16, v2
	s_and_b64 s[28:29], s[28:29], s[24:25]
	s_or_b64 s[26:27], s[26:27], s[28:29]
	s_sub_i32 s16, s16, s17
	s_max_i32 s16, s16, 0
	v_writelane_b32 v0, s26, 18
	v_writelane_b32 v1, s27, 18
	v_cmp_eq_u32_e64 s[24:25], s10, v51
	v_cmp_lt_u32_e64 s[26:27], s10, v51
	s_bcnt1_i32_b64 s17, s[24:25]
	s_nop 0
	v_mbcnt_lo_u32_b32 v2, s24, 0
	v_mbcnt_hi_u32_b32 v2, s25, v2
	v_cmp_gt_u32_e64 s[28:29], s16, v2
	s_and_b64 s[28:29], s[28:29], s[24:25]
	s_or_b64 s[26:27], s[26:27], s[28:29]
	s_sub_i32 s16, s16, s17
	s_max_i32 s16, s16, 0
	v_writelane_b32 v0, s26, 19
	v_writelane_b32 v1, s27, 19
	v_cmp_eq_u32_e64 s[24:25], s10, v52
	v_cmp_lt_u32_e64 s[26:27], s10, v52
	s_bcnt1_i32_b64 s17, s[24:25]
	s_nop 0
	v_mbcnt_lo_u32_b32 v2, s24, 0
	v_mbcnt_hi_u32_b32 v2, s25, v2
	v_cmp_gt_u32_e64 s[28:29], s16, v2
	s_and_b64 s[28:29], s[28:29], s[24:25]
	s_or_b64 s[26:27], s[26:27], s[28:29]
	s_sub_i32 s16, s16, s17
	s_max_i32 s16, s16, 0
	v_writelane_b32 v0, s26, 20
	v_writelane_b32 v1, s27, 20
	v_cmp_eq_u32_e64 s[24:25], s10, v53
	v_cmp_lt_u32_e64 s[26:27], s10, v53
	s_bcnt1_i32_b64 s17, s[24:25]
	s_nop 0
	v_mbcnt_lo_u32_b32 v2, s24, 0
	v_mbcnt_hi_u32_b32 v2, s25, v2
	v_cmp_gt_u32_e64 s[28:29], s16, v2
	s_and_b64 s[28:29], s[28:29], s[24:25]
	s_or_b64 s[26:27], s[26:27], s[28:29]
	s_sub_i32 s16, s16, s17
	s_max_i32 s16, s16, 0
	v_writelane_b32 v0, s26, 21
	v_writelane_b32 v1, s27, 21
	v_cmp_eq_u32_e64 s[24:25], s10, v54
	v_cmp_lt_u32_e64 s[26:27], s10, v54
	s_bcnt1_i32_b64 s17, s[24:25]
	s_nop 0
	v_mbcnt_lo_u32_b32 v2, s24, 0
	v_mbcnt_hi_u32_b32 v2, s25, v2
	v_cmp_gt_u32_e64 s[28:29], s16, v2
	s_and_b64 s[28:29], s[28:29], s[24:25]
	s_or_b64 s[26:27], s[26:27], s[28:29]
	s_sub_i32 s16, s16, s17
	s_max_i32 s16, s16, 0
	v_writelane_b32 v0, s26, 22
	v_writelane_b32 v1, s27, 22
	v_cmp_eq_u32_e64 s[24:25], s10, v55
	v_cmp_lt_u32_e64 s[26:27], s10, v55
	s_bcnt1_i32_b64 s17, s[24:25]
	s_nop 0
	v_mbcnt_lo_u32_b32 v2, s24, 0
	v_mbcnt_hi_u32_b32 v2, s25, v2
	v_cmp_gt_u32_e64 s[28:29], s16, v2
	s_and_b64 s[28:29], s[28:29], s[24:25]
	s_or_b64 s[26:27], s[26:27], s[28:29]
	s_sub_i32 s16, s16, s17
	s_max_i32 s16, s16, 0
	v_writelane_b32 v0, s26, 23
	v_writelane_b32 v1, s27, 23
	s_cmp_lt_u32 s21, 4
	s_cbranch_scc1 .Ltk_store
	v_cmp_eq_u32_e64 s[24:25], s10, v56
	v_cmp_lt_u32_e64 s[26:27], s10, v56
	s_bcnt1_i32_b64 s17, s[24:25]
	s_nop 0
	v_mbcnt_lo_u32_b32 v2, s24, 0
	v_mbcnt_hi_u32_b32 v2, s25, v2
	v_cmp_gt_u32_e64 s[28:29], s16, v2
	s_and_b64 s[28:29], s[28:29], s[24:25]
	s_or_b64 s[26:27], s[26:27], s[28:29]
	s_sub_i32 s16, s16, s17
	s_max_i32 s16, s16, 0
	v_writelane_b32 v0, s26, 24
	v_writelane_b32 v1, s27, 24
	v_cmp_eq_u32_e64 s[24:25], s10, v57
	v_cmp_lt_u32_e64 s[26:27], s10, v57
	s_bcnt1_i32_b64 s17, s[24:25]
	s_nop 0
	v_mbcnt_lo_u32_b32 v2, s24, 0
	v_mbcnt_hi_u32_b32 v2, s25, v2
	v_cmp_gt_u32_e64 s[28:29], s16, v2
	s_and_b64 s[28:29], s[28:29], s[24:25]
	s_or_b64 s[26:27], s[26:27], s[28:29]
	s_sub_i32 s16, s16, s17
	s_max_i32 s16, s16, 0
	v_writelane_b32 v0, s26, 25
	v_writelane_b32 v1, s27, 25
	v_cmp_eq_u32_e64 s[24:25], s10, v58
	v_cmp_lt_u32_e64 s[26:27], s10, v58
	s_bcnt1_i32_b64 s17, s[24:25]
	s_nop 0
	v_mbcnt_lo_u32_b32 v2, s24, 0
	v_mbcnt_hi_u32_b32 v2, s25, v2
	v_cmp_gt_u32_e64 s[28:29], s16, v2
	s_and_b64 s[28:29], s[28:29], s[24:25]
	s_or_b64 s[26:27], s[26:27], s[28:29]
	s_sub_i32 s16, s16, s17
	s_max_i32 s16, s16, 0
	v_writelane_b32 v0, s26, 26
	v_writelane_b32 v1, s27, 26
	v_cmp_eq_u32_e64 s[24:25], s10, v59
	v_cmp_lt_u32_e64 s[26:27], s10, v59
	s_bcnt1_i32_b64 s17, s[24:25]
	s_nop 0
	v_mbcnt_lo_u32_b32 v2, s24, 0
	v_mbcnt_hi_u32_b32 v2, s25, v2
	v_cmp_gt_u32_e64 s[28:29], s16, v2
	s_and_b64 s[28:29], s[28:29], s[24:25]
	s_or_b64 s[26:27], s[26:27], s[28:29]
	s_sub_i32 s16, s16, s17
	s_max_i32 s16, s16, 0
	v_writelane_b32 v0, s26, 27
	v_writelane_b32 v1, s27, 27
	v_cmp_eq_u32_e64 s[24:25], s10, v60
	v_cmp_lt_u32_e64 s[26:27], s10, v60
	s_bcnt1_i32_b64 s17, s[24:25]
	s_nop 0
	v_mbcnt_lo_u32_b32 v2, s24, 0
	v_mbcnt_hi_u32_b32 v2, s25, v2
	v_cmp_gt_u32_e64 s[28:29], s16, v2
	s_and_b64 s[28:29], s[28:29], s[24:25]
	s_or_b64 s[26:27], s[26:27], s[28:29]
	s_sub_i32 s16, s16, s17
	s_max_i32 s16, s16, 0
	v_writelane_b32 v0, s26, 28
	v_writelane_b32 v1, s27, 28
	v_cmp_eq_u32_e64 s[24:25], s10, v61
	v_cmp_lt_u32_e64 s[26:27], s10, v61
	s_bcnt1_i32_b64 s17, s[24:25]
	s_nop 0
	v_mbcnt_lo_u32_b32 v2, s24, 0
	v_mbcnt_hi_u32_b32 v2, s25, v2
	v_cmp_gt_u32_e64 s[28:29], s16, v2
	s_and_b64 s[28:29], s[28:29], s[24:25]
	s_or_b64 s[26:27], s[26:27], s[28:29]
	s_sub_i32 s16, s16, s17
	s_max_i32 s16, s16, 0
	v_writelane_b32 v0, s26, 29
	v_writelane_b32 v1, s27, 29
	v_cmp_eq_u32_e64 s[24:25], s10, v62
	v_cmp_lt_u32_e64 s[26:27], s10, v62
	s_bcnt1_i32_b64 s17, s[24:25]
	s_nop 0
	v_mbcnt_lo_u32_b32 v2, s24, 0
	v_mbcnt_hi_u32_b32 v2, s25, v2
	v_cmp_gt_u32_e64 s[28:29], s16, v2
	s_and_b64 s[28:29], s[28:29], s[24:25]
	s_or_b64 s[26:27], s[26:27], s[28:29]
	s_sub_i32 s16, s16, s17
	s_max_i32 s16, s16, 0
	v_writelane_b32 v0, s26, 30
	v_writelane_b32 v1, s27, 30
	v_cmp_eq_u32_e64 s[24:25], s10, v63
	v_cmp_lt_u32_e64 s[26:27], s10, v63
	s_bcnt1_i32_b64 s17, s[24:25]
	s_nop 0
	v_mbcnt_lo_u32_b32 v2, s24, 0
	v_mbcnt_hi_u32_b32 v2, s25, v2
	v_cmp_gt_u32_e64 s[28:29], s16, v2
	s_and_b64 s[28:29], s[28:29], s[24:25]
	s_or_b64 s[26:27], s[26:27], s[28:29]
	s_sub_i32 s16, s16, s17
	s_max_i32 s16, s16, 0
	v_writelane_b32 v0, s26, 31
	v_writelane_b32 v1, s27, 31
	s_branch .Ltk_store
